# grid barrier: non-leader workgroups poll the global release word directly instead of the per-XCD relay (one hop less)
# baseline (speedup 1.0000x reference)
.LBB0_103:
	s_or_b64 exec, exec, s[14:15]
	v_cvt_f32_u32_e32 v4, v2
	s_waitcnt vmcnt(0)
	buffer_inv sc1
	v_readfirstlane_b32 s12, v3
	v_sub_u32_e32 v3, 0, v2
	v_rcp_iflag_f32_e32 v4, v4
	v_add_u32_e32 v5, s12, v1
	v_mul_f32_e32 v4, 0x4f7ffffe, v4
	v_cvt_u32_f32_e32 v4, v4
	v_mul_lo_u32 v1, v3, v4
	v_mul_hi_u32 v1, v4, v1
	v_add_u32_e32 v1, v4, v1
	v_mul_hi_u32 v1, v5, v1
	v_mul_lo_u32 v3, v1, v2
	v_sub_u32_e32 v3, v5, v3
	v_add_u32_e32 v4, 1, v1
	v_cmp_ge_u32_e32 vcc, v3, v2
	s_nop 1
	v_cndmask_b32_e32 v1, v1, v4, vcc
	v_sub_u32_e32 v4, v3, v2
	v_cndmask_b32_e32 v3, v3, v4, vcc
	v_add_u32_e32 v4, 1, v1
	v_cmp_ge_u32_e32 vcc, v3, v2
	v_add_u32_e32 v3, 1, v5
	s_nop 0
	v_cndmask_b32_e32 v1, v1, v4, vcc
	v_mul_lo_u32 v4, v2, v1
	v_add_u32_e32 v2, v4, v2
	v_cmp_ne_u32_e32 vcc, v3, v2
	s_and_saveexec_b64 s[12:13], vcc
	s_xor_b64 s[12:13], exec, s[12:13]
	s_cbranch_execz .LBB0_117
	s_waitcnt lgkmcnt(0)
	s_add_u32 s18, s8, 0x1b06c500
	s_addc_u32 s19, s9, 0
	global_load_dword v0, v193, s[18:19] sc1
	s_waitcnt vmcnt(0)
	v_cmp_eq_u32_e32 vcc, v0, v1
	s_and_saveexec_b64 s[14:15], vcc
	s_cbranch_execz .LBB0_116
	s_add_u32 s16, s8, 0x1b069200
	s_addc_u32 s17, s9, 0
	s_mov_b32 s30, 1
	s_mov_b64 s[20:21], 0
	s_branch .LBB0_107

.LBB0_1188:
	s_or_b64 exec, exec, s[10:11]
	v_cvt_f32_u32_e32 v4, v2
	s_waitcnt vmcnt(0)
	buffer_inv sc1
	v_readfirstlane_b32 s8, v3
	v_sub_u32_e32 v3, 0, v2
	v_rcp_iflag_f32_e32 v4, v4
	v_add_u32_e32 v5, s8, v1
	v_mul_f32_e32 v4, 0x4f7ffffe, v4
	v_cvt_u32_f32_e32 v4, v4
	v_mul_lo_u32 v1, v3, v4
	v_mul_hi_u32 v1, v4, v1
	v_add_u32_e32 v1, v4, v1
	v_mul_hi_u32 v1, v5, v1
	v_mul_lo_u32 v3, v1, v2
	v_sub_u32_e32 v3, v5, v3
	v_add_u32_e32 v4, 1, v1
	v_cmp_ge_u32_e32 vcc, v3, v2
	s_nop 1
	v_cndmask_b32_e32 v1, v1, v4, vcc
	v_sub_u32_e32 v4, v3, v2
	v_cndmask_b32_e32 v3, v3, v4, vcc
	v_add_u32_e32 v4, 1, v1
	v_cmp_ge_u32_e32 vcc, v3, v2
	v_add_u32_e32 v3, 1, v5
	s_nop 0
	v_cndmask_b32_e32 v1, v1, v4, vcc
	v_mul_lo_u32 v4, v2, v1
	v_add_u32_e32 v2, v4, v2
	v_cmp_ne_u32_e32 vcc, v3, v2
	s_and_saveexec_b64 s[8:9], vcc
	s_xor_b64 s[8:9], exec, s[8:9]
	s_cbranch_execz .LBB0_1202
	s_waitcnt lgkmcnt(0)
	s_add_u32 s14, s2, 0x1b06c500
	s_addc_u32 s15, s3, 0
	global_load_dword v0, v193, s[14:15] sc1
	s_waitcnt vmcnt(0)
	v_cmp_eq_u32_e32 vcc, v0, v1
	s_and_saveexec_b64 s[10:11], vcc
	s_cbranch_execz .LBB0_1201
	s_add_u32 s12, s2, 0x1b069200
	s_addc_u32 s13, s3, 0
	s_mov_b32 s26, 1
	s_mov_b64 s[16:17], 0
	s_branch .LBB0_1192
